# indexer scoring loop software-pipelined: weighted sums and score write of chunk c-1 run under the LDS fragment reads of chunk c (two accumulator sets)
# baseline (speedup 1.0000x reference)
.Lidx_loop:
	v_add_u32_e32 v76, s11, v73
	ds_read_b128 v[118:121], v76
	ds_read_b128 v[126:129], v76 offset:4608
	ds_read_b128 v[114:117], v76 offset:32
	ds_read_b128 v[122:125], v76 offset:4640
	ds_read_b128 v[110:113], v76 offset:64
	ds_read_b128 v[106:109], v76 offset:4672
	ds_read_b128 v[86:89], v76 offset:4704
	ds_read_b128 v[102:105], v76 offset:96
	s_cmp_eq_u32 s2, 0
	s_cbranch_scc1 .Lidx_skipA
	v_max_i32_e32 v130, 0, v130
	v_max_i32_e32 v131, 0, v131
	v_max_i32_e32 v132, 0, v132
	v_max_i32_e32 v133, 0, v133
	v_max_i32_e32 v134, 0, v134
	v_max_i32_e32 v135, 0, v135
	v_max_i32_e32 v136, 0, v136
	v_max_i32_e32 v137, 0, v137
	v_max_i32_e32 v138, 0, v138
	v_max_i32_e32 v139, 0, v139
	v_max_i32_e32 v140, 0, v140
	v_max_i32_e32 v141, 0, v141
	v_max_i32_e32 v142, 0, v142
	v_max_i32_e32 v143, 0, v143
	v_max_i32_e32 v144, 0, v144
	v_max_i32_e32 v145, 0, v145
	v_max_i32_e32 v146, 0, v146
	v_max_i32_e32 v147, 0, v147
	v_max_i32_e32 v148, 0, v148
	v_max_i32_e32 v149, 0, v149
	v_max_i32_e32 v150, 0, v150
	v_max_i32_e32 v151, 0, v151
	v_max_i32_e32 v152, 0, v152
	v_max_i32_e32 v153, 0, v153
	v_max_i32_e32 v154, 0, v154
	v_max_i32_e32 v155, 0, v155
	v_max_i32_e32 v156, 0, v156
	v_max_i32_e32 v157, 0, v157
	v_max_i32_e32 v158, 0, v158
	v_max_i32_e32 v159, 0, v159
	v_max_i32_e32 v160, 0, v160
	v_max_i32_e32 v161, 0, v161
	v_pk_mul_f32 v[78:79], v[50:51], v[130:131]
	v_pk_mul_f32 v[80:81], v[58:59], v[138:139]
	v_pk_mul_f32 v[82:83], v[50:51], v[146:147]
	v_pk_mul_f32 v[84:85], v[58:59], v[154:155]
	v_pk_fma_f32 v[78:79], v[52:53], v[132:133], v[78:79]
	v_pk_fma_f32 v[80:81], v[60:61], v[140:141], v[80:81]
	v_pk_fma_f32 v[82:83], v[52:53], v[148:149], v[82:83]
	v_pk_fma_f32 v[84:85], v[60:61], v[156:157], v[84:85]
	v_pk_fma_f32 v[78:79], v[54:55], v[134:135], v[78:79]
	v_pk_fma_f32 v[80:81], v[62:63], v[142:143], v[80:81]
	v_pk_fma_f32 v[82:83], v[54:55], v[150:151], v[82:83]
	v_pk_fma_f32 v[84:85], v[62:63], v[158:159], v[84:85]
	v_pk_fma_f32 v[78:79], v[56:57], v[136:137], v[78:79]
	v_pk_fma_f32 v[80:81], v[64:65], v[144:145], v[80:81]
	v_pk_fma_f32 v[82:83], v[56:57], v[152:153], v[82:83]
	v_pk_fma_f32 v[84:85], v[64:65], v[160:161], v[84:85]
	v_add_f32_e32 v130, v78, v79
	v_add_f32_e32 v138, v80, v81
	v_add_f32_e32 v146, v82, v83
	v_add_f32_e32 v154, v84, v85
	s_nop 1
	v_permlane32_swap_b32_e32 v146, v154
	v_permlane32_swap_b32_e32 v130, v138
	v_add_f32_e32 v146, v146, v154
	v_add_f32_e32 v130, v130, v138
	ds_write2_b32 v251, v146, v130 offset1:32
	v_add_u32_e32 v251, 0x100, v251
.Lidx_skipA:
	s_waitcnt lgkmcnt(6)
	v_mfma_f32_32x32x16_bf16 v[18:33], v[34:37], v[118:121], 0
	v_mfma_f32_32x32x16_bf16 v[2:17], v[34:37], v[126:129], 0
	s_waitcnt lgkmcnt(4)
	v_mfma_f32_32x32x16_bf16 v[18:33], v[38:41], v[114:117], v[18:33]
	v_mfma_f32_32x32x16_bf16 v[2:17], v[38:41], v[122:125], v[2:17]
	s_waitcnt lgkmcnt(2)
	v_mfma_f32_32x32x16_bf16 v[18:33], v[42:45], v[110:113], v[18:33]
	v_mfma_f32_32x32x16_bf16 v[2:17], v[42:45], v[106:109], v[2:17]
	s_waitcnt lgkmcnt(0)
	v_mfma_f32_32x32x16_bf16 v[2:17], v[46:49], v[86:89], v[2:17]
	v_mfma_f32_32x32x16_bf16 v[18:33], v[46:49], v[102:105], v[18:33]
	s_add_i32 s0, s2, 1
	s_cmp_ge_u32 s0, s8
	s_cbranch_scc1 .Lidx_nostA
	s_xor_b32 s11, s11, 0x2400
	s_waitcnt vmcnt(0)
	v_add_u32_e32 v76, s11, v72
	ds_write_b128 v76, v[66:69]
	s_add_i32 s0, s2, 2
	s_cmp_ge_u32 s0, s8
	s_cbranch_scc1 .Lidx_nostA
	global_load_dwordx4 v[66:69], v[70:71], off
	v_lshl_add_u64 v[70:71], v[70:71], 0, s[12:13]
.Lidx_nostA:
	s_add_i32 s2, s2, 1
	s_cmp_ge_u32 s2, s8
	s_cbranch_scc1 .Lidx_fin0
	s_waitcnt lgkmcnt(0)
	s_barrier
	v_add_u32_e32 v76, s11, v73
	ds_read_b128 v[118:121], v76
	ds_read_b128 v[126:129], v76 offset:4608
	ds_read_b128 v[114:117], v76 offset:32
	ds_read_b128 v[122:125], v76 offset:4640
	ds_read_b128 v[110:113], v76 offset:64
	ds_read_b128 v[106:109], v76 offset:4672
	ds_read_b128 v[86:89], v76 offset:4704
	ds_read_b128 v[102:105], v76 offset:96
	v_max_i32_e32 v2, 0, v2
	v_max_i32_e32 v3, 0, v3
	v_max_i32_e32 v4, 0, v4
	v_max_i32_e32 v5, 0, v5
	v_max_i32_e32 v6, 0, v6
	v_max_i32_e32 v7, 0, v7
	v_max_i32_e32 v8, 0, v8
	v_max_i32_e32 v9, 0, v9
	v_max_i32_e32 v10, 0, v10
	v_max_i32_e32 v11, 0, v11
	v_max_i32_e32 v12, 0, v12
	v_max_i32_e32 v13, 0, v13
	v_max_i32_e32 v14, 0, v14
	v_max_i32_e32 v15, 0, v15
	v_max_i32_e32 v16, 0, v16
	v_max_i32_e32 v17, 0, v17
	v_max_i32_e32 v18, 0, v18
	v_max_i32_e32 v19, 0, v19
	v_max_i32_e32 v20, 0, v20
	v_max_i32_e32 v21, 0, v21
	v_max_i32_e32 v22, 0, v22
	v_max_i32_e32 v23, 0, v23
	v_max_i32_e32 v24, 0, v24
	v_max_i32_e32 v25, 0, v25
	v_max_i32_e32 v26, 0, v26
	v_max_i32_e32 v27, 0, v27
	v_max_i32_e32 v28, 0, v28
	v_max_i32_e32 v29, 0, v29
	v_max_i32_e32 v30, 0, v30
	v_max_i32_e32 v31, 0, v31
	v_max_i32_e32 v32, 0, v32
	v_max_i32_e32 v33, 0, v33
	v_pk_mul_f32 v[78:79], v[50:51], v[2:3]
	v_pk_mul_f32 v[80:81], v[58:59], v[10:11]
	v_pk_mul_f32 v[82:83], v[50:51], v[18:19]
	v_pk_mul_f32 v[84:85], v[58:59], v[26:27]
	v_pk_fma_f32 v[78:79], v[52:53], v[4:5], v[78:79]
	v_pk_fma_f32 v[80:81], v[60:61], v[12:13], v[80:81]
	v_pk_fma_f32 v[82:83], v[52:53], v[20:21], v[82:83]
	v_pk_fma_f32 v[84:85], v[60:61], v[28:29], v[84:85]
	v_pk_fma_f32 v[78:79], v[54:55], v[6:7], v[78:79]
	v_pk_fma_f32 v[80:81], v[62:63], v[14:15], v[80:81]
	v_pk_fma_f32 v[82:83], v[54:55], v[22:23], v[82:83]
	v_pk_fma_f32 v[84:85], v[62:63], v[30:31], v[84:85]
	v_pk_fma_f32 v[78:79], v[56:57], v[8:9], v[78:79]
	v_pk_fma_f32 v[80:81], v[64:65], v[16:17], v[80:81]
	v_pk_fma_f32 v[82:83], v[56:57], v[24:25], v[82:83]
	v_pk_fma_f32 v[84:85], v[64:65], v[32:33], v[84:85]
	v_add_f32_e32 v2, v78, v79
	v_add_f32_e32 v10, v80, v81
	v_add_f32_e32 v18, v82, v83
	v_add_f32_e32 v26, v84, v85
	s_nop 1
	v_permlane32_swap_b32_e32 v18, v26
	v_permlane32_swap_b32_e32 v2, v10
	v_add_f32_e32 v18, v18, v26
	v_add_f32_e32 v2, v2, v10
	ds_write2_b32 v251, v18, v2 offset1:32
	v_add_u32_e32 v251, 0x100, v251
	s_waitcnt lgkmcnt(6)
	v_mfma_f32_32x32x16_bf16 v[146:161], v[34:37], v[118:121], 0
	v_mfma_f32_32x32x16_bf16 v[130:145], v[34:37], v[126:129], 0
	s_waitcnt lgkmcnt(4)
	v_mfma_f32_32x32x16_bf16 v[146:161], v[38:41], v[114:117], v[146:161]
	v_mfma_f32_32x32x16_bf16 v[130:145], v[38:41], v[122:125], v[130:145]
	s_waitcnt lgkmcnt(2)
	v_mfma_f32_32x32x16_bf16 v[146:161], v[42:45], v[110:113], v[146:161]
	v_mfma_f32_32x32x16_bf16 v[130:145], v[42:45], v[106:109], v[130:145]
	s_waitcnt lgkmcnt(0)
	v_mfma_f32_32x32x16_bf16 v[130:145], v[46:49], v[86:89], v[130:145]
	v_mfma_f32_32x32x16_bf16 v[146:161], v[46:49], v[102:105], v[146:161]
	s_add_i32 s0, s2, 1
	s_cmp_ge_u32 s0, s8
	s_cbranch_scc1 .Lidx_nostB
	s_xor_b32 s11, s11, 0x2400
	s_waitcnt vmcnt(0)
	v_add_u32_e32 v76, s11, v72
	ds_write_b128 v76, v[66:69]
	s_add_i32 s0, s2, 2
	s_cmp_ge_u32 s0, s8
	s_cbranch_scc1 .Lidx_nostB
	global_load_dwordx4 v[66:69], v[70:71], off
	v_lshl_add_u64 v[70:71], v[70:71], 0, s[12:13]
.Lidx_nostB:
	s_add_i32 s2, s2, 1
	s_cmp_ge_u32 s2, s8
	s_cbranch_scc1 .Lidx_fin1
	s_waitcnt lgkmcnt(0)
	s_barrier
	s_branch .Lidx_loop
.Lidx_fin0:
	s_nop 10
	v_max_i32_e32 v2, 0, v2
	v_max_i32_e32 v3, 0, v3
	v_max_i32_e32 v4, 0, v4
	v_max_i32_e32 v5, 0, v5
	v_max_i32_e32 v6, 0, v6
	v_max_i32_e32 v7, 0, v7
	v_max_i32_e32 v8, 0, v8
	v_max_i32_e32 v9, 0, v9
	v_max_i32_e32 v10, 0, v10
	v_max_i32_e32 v11, 0, v11
	v_max_i32_e32 v12, 0, v12
	v_max_i32_e32 v13, 0, v13
	v_max_i32_e32 v14, 0, v14
	v_max_i32_e32 v15, 0, v15
	v_max_i32_e32 v16, 0, v16
	v_max_i32_e32 v17, 0, v17
	v_max_i32_e32 v18, 0, v18
	v_max_i32_e32 v19, 0, v19
	v_max_i32_e32 v20, 0, v20
	v_max_i32_e32 v21, 0, v21
	v_max_i32_e32 v22, 0, v22
	v_max_i32_e32 v23, 0, v23
	v_max_i32_e32 v24, 0, v24
	v_max_i32_e32 v25, 0, v25
	v_max_i32_e32 v26, 0, v26
	v_max_i32_e32 v27, 0, v27
	v_max_i32_e32 v28, 0, v28
	v_max_i32_e32 v29, 0, v29
	v_max_i32_e32 v30, 0, v30
	v_max_i32_e32 v31, 0, v31
	v_max_i32_e32 v32, 0, v32
	v_max_i32_e32 v33, 0, v33
	v_pk_mul_f32 v[78:79], v[50:51], v[2:3]
	v_pk_mul_f32 v[80:81], v[58:59], v[10:11]
	v_pk_mul_f32 v[82:83], v[50:51], v[18:19]
	v_pk_mul_f32 v[84:85], v[58:59], v[26:27]
	v_pk_fma_f32 v[78:79], v[52:53], v[4:5], v[78:79]
	v_pk_fma_f32 v[80:81], v[60:61], v[12:13], v[80:81]
	v_pk_fma_f32 v[82:83], v[52:53], v[20:21], v[82:83]
	v_pk_fma_f32 v[84:85], v[60:61], v[28:29], v[84:85]
	v_pk_fma_f32 v[78:79], v[54:55], v[6:7], v[78:79]
	v_pk_fma_f32 v[80:81], v[62:63], v[14:15], v[80:81]
	v_pk_fma_f32 v[82:83], v[54:55], v[22:23], v[82:83]
	v_pk_fma_f32 v[84:85], v[62:63], v[30:31], v[84:85]
	v_pk_fma_f32 v[78:79], v[56:57], v[8:9], v[78:79]
	v_pk_fma_f32 v[80:81], v[64:65], v[16:17], v[80:81]
	v_pk_fma_f32 v[82:83], v[56:57], v[24:25], v[82:83]
	v_pk_fma_f32 v[84:85], v[64:65], v[32:33], v[84:85]
	v_add_f32_e32 v2, v78, v79
	v_add_f32_e32 v10, v80, v81
	v_add_f32_e32 v18, v82, v83
	v_add_f32_e32 v26, v84, v85
	s_nop 1
	v_permlane32_swap_b32_e32 v18, v26
	v_permlane32_swap_b32_e32 v2, v10
	v_add_f32_e32 v18, v18, v26
	v_add_f32_e32 v2, v2, v10
	ds_write2_b32 v251, v18, v2 offset1:32
	v_add_u32_e32 v251, 0x100, v251
	s_branch .Lidx_done
.Lidx_fin1:
	s_nop 10
	v_max_i32_e32 v130, 0, v130
	v_max_i32_e32 v131, 0, v131
	v_max_i32_e32 v132, 0, v132
	v_max_i32_e32 v133, 0, v133
	v_max_i32_e32 v134, 0, v134
	v_max_i32_e32 v135, 0, v135
	v_max_i32_e32 v136, 0, v136
	v_max_i32_e32 v137, 0, v137
	v_max_i32_e32 v138, 0, v138
	v_max_i32_e32 v139, 0, v139
	v_max_i32_e32 v140, 0, v140
	v_max_i32_e32 v141, 0, v141
	v_max_i32_e32 v142, 0, v142
	v_max_i32_e32 v143, 0, v143
	v_max_i32_e32 v144, 0, v144
	v_max_i32_e32 v145, 0, v145
	v_max_i32_e32 v146, 0, v146
	v_max_i32_e32 v147, 0, v147
	v_max_i32_e32 v148, 0, v148
	v_max_i32_e32 v149, 0, v149
	v_max_i32_e32 v150, 0, v150
	v_max_i32_e32 v151, 0, v151
	v_max_i32_e32 v152, 0, v152
	v_max_i32_e32 v153, 0, v153
	v_max_i32_e32 v154, 0, v154
	v_max_i32_e32 v155, 0, v155
	v_max_i32_e32 v156, 0, v156
	v_max_i32_e32 v157, 0, v157
	v_max_i32_e32 v158, 0, v158
	v_max_i32_e32 v159, 0, v159
	v_max_i32_e32 v160, 0, v160
	v_max_i32_e32 v161, 0, v161
	v_pk_mul_f32 v[78:79], v[50:51], v[130:131]
	v_pk_mul_f32 v[80:81], v[58:59], v[138:139]
	v_pk_mul_f32 v[82:83], v[50:51], v[146:147]
	v_pk_mul_f32 v[84:85], v[58:59], v[154:155]
	v_pk_fma_f32 v[78:79], v[52:53], v[132:133], v[78:79]
	v_pk_fma_f32 v[80:81], v[60:61], v[140:141], v[80:81]
	v_pk_fma_f32 v[82:83], v[52:53], v[148:149], v[82:83]
	v_pk_fma_f32 v[84:85], v[60:61], v[156:157], v[84:85]
	v_pk_fma_f32 v[78:79], v[54:55], v[134:135], v[78:79]
	v_pk_fma_f32 v[80:81], v[62:63], v[142:143], v[80:81]
	v_pk_fma_f32 v[82:83], v[54:55], v[150:151], v[82:83]
	v_pk_fma_f32 v[84:85], v[62:63], v[158:159], v[84:85]
	v_pk_fma_f32 v[78:79], v[56:57], v[136:137], v[78:79]
	v_pk_fma_f32 v[80:81], v[64:65], v[144:145], v[80:81]
	v_pk_fma_f32 v[82:83], v[56:57], v[152:153], v[82:83]
	v_pk_fma_f32 v[84:85], v[64:65], v[160:161], v[84:85]
	v_add_f32_e32 v130, v78, v79
	v_add_f32_e32 v138, v80, v81
	v_add_f32_e32 v146, v82, v83
	v_add_f32_e32 v154, v84, v85
	s_nop 1
	v_permlane32_swap_b32_e32 v146, v154
	v_permlane32_swap_b32_e32 v130, v138
	v_add_f32_e32 v146, v146, v154
	v_add_f32_e32 v130, v130, v138
	ds_write2_b32 v251, v146, v130 offset1:32
	v_add_u32_e32 v251, 0x100, v251
